# SSD S1: B^T scaling and both G tiles use packed f32 mul/sub (same ops), one bf16 cvt per two values with ds_write_b16_d16_hi; 28 fewer VALU per chunk per wave
# speedup vs baseline: 1.0001x; 1.0001x over previous
; #define LAS __attribute__((address_space(3)))
; __device__ __forceinline__ unsigned pk2(float lo, float hi) { unsigned r; asm("v_cvt_pk_bf16_f32 %0, %1, %2" : "=v"(r) : "v"(lo), "v"(hi)); return r; }
; __device__ __forceinline__ bf16_t f2bf(float f) { return (bf16_t)(pk2(f, 0.f) & 0xffffu); }
; __device__ __forceinline__ float bflo(unsigned w) { return __uint_as_float(w << 16); }
; __device__ __forceinline__ void ssd_item(const Args& a, LAS unsigned char* lds, int layer, bool is_sample, int b, int h, int seq_row0, int nchunks,
;                                          bf16_t* proj, float* ssq, const int tid) {
;     ...
;         {
;             float o[8];
; #pragma unroll
;             for (int i = 0; i < 8; ++i) o[i] = cb[i];
; #pragma unroll
;             for (int k = 0; k < 4; ++k) { const u32x4 w = *(const LAS u32x4*)(lds + L_XRAW + (lane + k) * P64 + wave * 16);
;                 o[0] += cw[k][0] * bflo(w.x); o[1] += cw[k][1] * bfhi(w.x); o[2] += cw[k][2] * bflo(w.y); o[3] += cw[k][3] * bfhi(w.y);
;                 o[4] += cw[k][4] * bflo(w.z); o[5] += cw[k][5] * bfhi(w.z); o[6] += cw[k][6] * bflo(w.w); o[7] += cw[k][7] * bfhi(w.w); }
; #pragma unroll
;             for (int i = 0; i < 8; ++i) *(LAS bf16_t*)(lds + L_XST + (wave * 8 + i) * P64 + lane * 2) = f2bf(siluf_(o[i]));
;         }
;         {
;             const int oc = tid & 15, tk = (tid >> 4) * 2;
;             const float a63s = acv[63]; const float wa = dtv[tk] * __builtin_amdgcn_exp2f(a63s - acv[tk]), wb = dtv[tk + 1] * __builtin_amdgcn_exp2f(a63s - acv[tk + 1]);
;             LAS unsigned char* d = lds + L_BWT + (oc * 8) * P64 + ((((tk >> 3) ^ ((oc >> 1) & 7)) << 4) | ((tk * 2) & 15));
;             *(LAS unsigned*)(d + 0 * P64) = pk2(bflo(bo0.x) * wa, bflo(bo1.x) * wb); *(LAS unsigned*)(d + 1 * P64) = pk2(bfhi(bo0.x) * wa, bfhi(bo1.x) * wb);
;             *(LAS unsigned*)(d + 2 * P64) = pk2(bflo(bo0.y) * wa, bflo(bo1.y) * wb); *(LAS unsigned*)(d + 3 * P64) = pk2(bfhi(bo0.y) * wa, bfhi(bo1.y) * wb);
;             *(LAS unsigned*)(d + 4 * P64) = pk2(bflo(bo0.z) * wa, bflo(bo1.z) * wb); *(LAS unsigned*)(d + 5 * P64) = pk2(bfhi(bo0.z) * wa, bfhi(bo1.z) * wb);
;             *(LAS unsigned*)(d + 6 * P64) = pk2(bflo(bo0.w) * wa, bflo(bo1.w) * wb); *(LAS unsigned*)(d + 7 * P64) = pk2(bfhi(bo0.w) * wa, bfhi(bo1.w) * wb);
.LBB0_570:
	ds_read_b128 v[176:179], v123
	ds_read_b128 v[180:183], v123 offset:144
	ds_read_b128 v[184:187], v123 offset:288
	ds_read_b128 v[188:191], v123 offset:432
	s_add_i32 s65, s15, 0
	s_add_i32 s65, s65, 0x1c73c
	v_add_u32_e32 v164, v110, v192
	v_add_u32_e32 v149, s15, v120
	v_add_u32_e32 v151, s15, v119
	v_mov_b32_e32 v148, s65
	v_add_u32_e32 v150, 0x1a640, v149
	v_add_u32_e32 v149, 0x1c640, v149
	v_add_u32_e32 v152, 0x1a640, v151
	v_add_u32_e32 v151, 0x1c640, v151
	ds_read_b32 v148, v148
	ds_read_b32 v150, v150
	ds_read_b32 v149, v149
	ds_read_b32 v152, v152
	ds_read_b32 v151, v151
	v_add_u32_e32 v165, s15, v117
	s_waitcnt lgkmcnt(8)
	v_lshlrev_b32_e32 v216, 16, v176
	v_and_b32_e32 v217, 0xffff0000, v176
	v_lshlrev_b32_e32 v218, 16, v177
	v_and_b32_e32 v219, 0xffff0000, v177
	v_lshlrev_b32_e32 v220, 16, v178
	v_and_b32_e32 v221, 0xffff0000, v178
	v_lshlrev_b32_e32 v222, 16, v179
	v_and_b32_e32 v223, 0xffff0000, v179
	v_pk_fma_f32 v[102:103], v[6:7], v[216:217], v[38:39]
	v_pk_fma_f32 v[156:157], v[8:9], v[218:219], v[40:41]
	v_pk_fma_f32 v[158:159], v[2:3], v[220:221], v[34:35]
	v_pk_fma_f32 v[160:161], v[4:5], v[222:223], v[36:37]
	s_waitcnt lgkmcnt(7)
	v_lshlrev_b32_e32 v216, 16, v180
	v_and_b32_e32 v217, 0xffff0000, v180
	v_lshlrev_b32_e32 v218, 16, v181
	v_and_b32_e32 v219, 0xffff0000, v181
	v_lshlrev_b32_e32 v220, 16, v182
	v_and_b32_e32 v221, 0xffff0000, v182
	v_lshlrev_b32_e32 v222, 16, v183
	v_and_b32_e32 v223, 0xffff0000, v183
	v_pk_fma_f32 v[102:103], v[10:11], v[216:217], v[102:103]
	v_pk_fma_f32 v[156:157], v[12:13], v[218:219], v[156:157]
	v_pk_fma_f32 v[158:159], v[14:15], v[220:221], v[158:159]
	v_pk_fma_f32 v[160:161], v[16:17], v[222:223], v[160:161]
	s_waitcnt lgkmcnt(6)
	v_lshlrev_b32_e32 v216, 16, v184
	v_and_b32_e32 v217, 0xffff0000, v184
	v_lshlrev_b32_e32 v218, 16, v185
	v_and_b32_e32 v219, 0xffff0000, v185
	v_lshlrev_b32_e32 v220, 16, v186
	v_and_b32_e32 v221, 0xffff0000, v186
	v_lshlrev_b32_e32 v222, 16, v187
	v_and_b32_e32 v223, 0xffff0000, v187
	v_pk_fma_f32 v[102:103], v[18:19], v[216:217], v[102:103]
	v_pk_fma_f32 v[156:157], v[20:21], v[218:219], v[156:157]
	v_pk_fma_f32 v[158:159], v[22:23], v[220:221], v[158:159]
	v_pk_fma_f32 v[160:161], v[24:25], v[222:223], v[160:161]
	s_waitcnt lgkmcnt(5)
	v_lshlrev_b32_e32 v216, 16, v188
	v_and_b32_e32 v217, 0xffff0000, v188
	v_lshlrev_b32_e32 v218, 16, v189
	v_and_b32_e32 v219, 0xffff0000, v189
	v_lshlrev_b32_e32 v220, 16, v190
	v_and_b32_e32 v221, 0xffff0000, v190
	v_lshlrev_b32_e32 v222, 16, v191
	v_and_b32_e32 v223, 0xffff0000, v191
	v_pk_fma_f32 v[102:103], v[26:27], v[216:217], v[102:103]
	v_pk_fma_f32 v[156:157], v[28:29], v[218:219], v[156:157]
	v_pk_fma_f32 v[158:159], v[30:31], v[220:221], v[158:159]
	v_pk_fma_f32 v[160:161], v[32:33], v[222:223], v[160:161]
	v_mul_f32_e32 v224, 0xbfb8aa3b, v102
	v_mul_f32_e32 v225, 0xbfb8aa3b, v103
	v_mul_f32_e32 v226, 0xbfb8aa3b, v156
	v_mul_f32_e32 v227, 0xbfb8aa3b, v157
	v_mul_f32_e32 v228, 0xbfb8aa3b, v158
	v_mul_f32_e32 v229, 0xbfb8aa3b, v159
	v_mul_f32_e32 v230, 0xbfb8aa3b, v160
	v_mul_f32_e32 v231, 0xbfb8aa3b, v161
	v_exp_f32_e32 v224, v224
	v_exp_f32_e32 v225, v225
	v_exp_f32_e32 v226, v226
	v_exp_f32_e32 v227, v227
	v_exp_f32_e32 v228, v228
	v_exp_f32_e32 v229, v229
	v_exp_f32_e32 v230, v230
	v_exp_f32_e32 v231, v231
	v_pk_add_f32 v[224:225], v[224:225], 1.0 op_sel_hi:[1,0]
	v_pk_add_f32 v[226:227], v[226:227], 1.0 op_sel_hi:[1,0]
	v_pk_add_f32 v[228:229], v[228:229], 1.0 op_sel_hi:[1,0]
	v_pk_add_f32 v[230:231], v[230:231], 1.0 op_sel_hi:[1,0]
	v_rcp_f32_e32 v224, v224
	v_rcp_f32_e32 v225, v225
	v_rcp_f32_e32 v226, v226
	v_rcp_f32_e32 v227, v227
	v_rcp_f32_e32 v228, v228
	v_rcp_f32_e32 v229, v229
	v_rcp_f32_e32 v230, v230
	v_rcp_f32_e32 v231, v231
	v_pk_mul_f32 v[102:103], v[102:103], v[224:225]
	v_pk_mul_f32 v[156:157], v[156:157], v[226:227]
	v_pk_mul_f32 v[158:159], v[158:159], v[228:229]
	v_pk_mul_f32 v[160:161], v[160:161], v[230:231]
	v_cvt_pk_bf16_f32 v232, v102, v103
	v_cvt_pk_bf16_f32 v233, v156, v157
	v_cvt_pk_bf16_f32 v234, v158, v159
	v_cvt_pk_bf16_f32 v235, v160, v161
	ds_write_b16 v124, v232
	ds_write_b16_d16_hi v124, v232 offset:144
	ds_write_b16 v124, v233 offset:288
	ds_write_b16_d16_hi v124, v233 offset:432
	ds_write_b16 v194, v234 offset:576
	ds_write_b16_d16_hi v194, v234 offset:720
	ds_write_b16 v194, v235 offset:864
	ds_write_b16_d16_hi v194, v235 offset:1008
	s_waitcnt lgkmcnt(12)
	s_waitcnt lgkmcnt(10)
	v_sub_f32_e32 v103, v148, v149
	s_waitcnt lgkmcnt(8)
	v_sub_f32_e32 v148, v148, v151
	v_exp_f32_e32 v103, v103
	v_exp_f32_e32 v148, v148
	v_mul_f32_e32 v102, v150, v103
	v_mul_f32_e32 v103, v152, v148
	v_add_u32_e32 v224, 0xd000, v125
	v_lshlrev_b32_e32 v216, 16, v58
	v_lshlrev_b32_e32 v217, 16, v62
	v_and_b32_e32 v218, 0xffff0000, v58
	v_and_b32_e32 v219, 0xffff0000, v62
	v_pk_mul_f32 v[216:217], v[102:103], v[216:217]
	v_pk_mul_f32 v[218:219], v[102:103], v[218:219]
	v_cvt_pk_bf16_f32 v220, v216, v217
	v_cvt_pk_bf16_f32 v221, v218, v219
	ds_write2_b32 v224, v220, v221 offset1:36
	v_lshlrev_b32_e32 v216, 16, v59
	v_lshlrev_b32_e32 v217, 16, v63
	v_and_b32_e32 v218, 0xffff0000, v59
	v_and_b32_e32 v219, 0xffff0000, v63
	v_pk_mul_f32 v[216:217], v[102:103], v[216:217]
	v_pk_mul_f32 v[218:219], v[102:103], v[218:219]
	v_cvt_pk_bf16_f32 v222, v216, v217
	v_cvt_pk_bf16_f32 v223, v218, v219
	ds_write2_b32 v224, v222, v223 offset0:72 offset1:108
	v_lshlrev_b32_e32 v216, 16, v60
	v_lshlrev_b32_e32 v217, 16, v64
	v_and_b32_e32 v218, 0xffff0000, v60
	v_and_b32_e32 v219, 0xffff0000, v64
	v_pk_mul_f32 v[216:217], v[102:103], v[216:217]
	v_pk_mul_f32 v[218:219], v[102:103], v[218:219]
	v_cvt_pk_bf16_f32 v220, v216, v217
	v_cvt_pk_bf16_f32 v221, v218, v219
	ds_write2_b32 v224, v220, v221 offset0:144 offset1:180
	v_lshlrev_b32_e32 v216, 16, v61
	v_lshlrev_b32_e32 v217, 16, v65
	v_and_b32_e32 v218, 0xffff0000, v61
	v_and_b32_e32 v219, 0xffff0000, v65
	v_pk_mul_f32 v[216:217], v[102:103], v[216:217]
	v_pk_mul_f32 v[218:219], v[102:103], v[218:219]
	v_cvt_pk_bf16_f32 v222, v216, v217
	v_cvt_pk_bf16_f32 v223, v218, v219
	ds_write2_b32 v224, v222, v223 offset0:216 offset1:252
	ds_read_b128 v[58:61], v164 offset:18432
	v_add_u32_e32 v102, v111, v192
	ds_read_b128 v[62:65], v102 offset:35840
	ds_read_b128 v[148:151], v164 offset:18496
	ds_read_b128 v[152:155], v164 offset:18624
	s_waitcnt lgkmcnt(2)
; #define LAS __attribute__((address_space(3)))
; __device__ __forceinline__ bf16_t f2bf(float f) { return (bf16_t)(pk2(f, 0.f) & 0xffffu); }
; __device__ __forceinline__ f32x4 mfma16(bf16x8 a, bf16x8 b, f32x4 c) { return __builtin_amdgcn_mfma_f32_16x16x32_bf16(a, b, c, 0, 0, 0); }
; #define LBAR() do { asm volatile("s_waitcnt lgkmcnt(0)" ::: "memory"); __builtin_amdgcn_s_barrier(); asm volatile("" ::: "memory"); } while (0)
; __device__ __forceinline__ void ssd_item(const Args& a, LAS unsigned char* lds, int layer, bool is_sample, int b, int h, int seq_row0, int nchunks,
;                                          bf16_t* proj, float* ssq, const int tid) {
;     ...
;         {
;             float al[4];
; #pragma unroll
;             for (int j = 0; j < 4; ++j) al[j] = acv[16 * rb + 4 * fq + j];
; #pragma unroll
;             for (int ci = 0; ci < 2; ++ci) { const int cbk = (wave & 1) * 2 + ci; f32x4 acc = (f32x4){0.f, 0.f, 0.f, 0.f};
; #pragma unroll
;                 for (int ks = 0; ks < 4; ++ks) { const bf16x8 av = *(const LAS bf16x8*)(lds + L_CM + (16 * rb + fr) * P128 + (32 * ks + 8 * fq) * 2);
;                     const bf16x8 bv = *(const LAS bf16x8*)(lds + L_BM + (16 * cbk + fr) * P128 + (32 * ks + 8 * fq) * 2); acc = mfma16(av, bv, acc); }
;                 const int s = 16 * cbk + fr; const float as = acv[s], ds = dtv[s];
; #pragma unroll
;                 for (int j = 0; j < 4; ++j) { const int l = 16 * rb + 4 * fq + j;
;                     const float gv = (s <= l) ? acc[j] * __builtin_amdgcn_exp2f(al[j] - as) * ds : 0.f;
;                     *(LAS bf16_t*)(lds + L_G + l * P64 + s * 2) = f2bf(gv); } }
;         }
;         LBAR();
	v_mfma_f32_16x16x32_bf16 v[58:61], v[58:61], v[62:65], 0
	ds_read_b128 v[62:65], v164 offset:18560
	ds_read_b128 v[156:159], v102 offset:35904
	ds_read_b128 v[160:163], v102 offset:35968
	v_add_u32_e32 v103, s15, v118
	v_add_u32_e32 v103, 0x1c640, v103
	s_waitcnt lgkmcnt(1)
	v_mfma_f32_16x16x32_bf16 v[58:61], v[148:151], v[156:159], v[58:61]
	ds_read_b128 v[148:151], v103
	v_add_u32_e32 v157, 0x1a640, v165
	v_add_u32_e32 v158, 0x1c680, v165
	s_waitcnt lgkmcnt(1)
	v_mfma_f32_16x16x32_bf16 v[58:61], v[62:65], v[160:163], v[58:61]
	v_add_u32_e32 v62, 0x1c640, v165
	ds_read_b32 v156, v62
	ds_read_b128 v[62:65], v102 offset:36032
	ds_read_b32 v102, v157
	ds_read_b32 v169, v158
	s_waitcnt lgkmcnt(2)
	v_mfma_f32_16x16x32_bf16 v[58:61], v[152:155], v[62:65], v[58:61]
	v_pk_add_f32 v[216:217], v[148:149], v[156:157] op_sel_hi:[1,0] neg_lo:[0,1] neg_hi:[0,1]
	v_pk_add_f32 v[218:219], v[150:151], v[156:157] op_sel_hi:[1,0] neg_lo:[0,1] neg_hi:[0,1]
	v_exp_f32_e32 v216, v216
	v_exp_f32_e32 v217, v217
	v_exp_f32_e32 v218, v218
	v_exp_f32_e32 v219, v219
	v_add_u32_e32 v63, v112, v195
	s_nop 2
	v_pk_mul_f32 v[58:59], v[58:59], v[216:217]
	v_pk_mul_f32 v[60:61], v[60:61], v[218:219]
	s_waitcnt lgkmcnt(1)
	v_pk_mul_f32 v[58:59], v[102:103], v[58:59] op_sel_hi:[0,1]
	v_pk_mul_f32 v[60:61], v[102:103], v[60:61] op_sel_hi:[0,1]
	v_cndmask_b32_e64 v58, v58, 0, s[40:41]
	v_cndmask_b32_e64 v59, v59, 0, s[42:43]
	v_cndmask_b32_e64 v60, v60, 0, s[44:45]
	v_cndmask_b32_e64 v61, v61, 0, s[46:47]
	v_cvt_pk_bf16_f32 v58, v58, v59
	v_cvt_pk_bf16_f32 v60, v60, v61
	ds_write_b16 v63, v58 offset:9216
	ds_write_b16_d16_hi v63, v58 offset:9360
	ds_write_b16 v63, v60 offset:9504
	ds_write_b16_d16_hi v63, v60 offset:9648
	ds_read_b128 v[58:61], v164 offset:18432
	v_add_u32_e32 v102, v114, v192
	ds_read_b128 v[62:65], v164 offset:18496
	ds_read_b128 v[152:155], v102 offset:35840
	ds_read_b128 v[156:159], v102 offset:35904
	s_waitcnt lgkmcnt(1)
	v_mfma_f32_16x16x32_bf16 v[58:61], v[58:61], v[152:155], 0
	ds_read_b128 v[152:155], v164 offset:18560
	s_waitcnt lgkmcnt(1)
	v_mfma_f32_16x16x32_bf16 v[58:61], v[62:65], v[156:159], v[58:61]
	ds_read_b128 v[62:65], v102 offset:35968
	ds_read_b128 v[156:159], v164 offset:18624
	ds_read_b128 v[160:163], v102 offset:36032
	s_waitcnt lgkmcnt(2)
	v_mfma_f32_16x16x32_bf16 v[58:61], v[152:155], v[62:65], v[58:61]
	v_pk_add_f32 v[216:217], v[148:149], v[168:169] op_sel:[0,1] op_sel_hi:[1,1] neg_lo:[0,1] neg_hi:[0,1]
	v_pk_add_f32 v[218:219], v[150:151], v[168:169] op_sel:[0,1] op_sel_hi:[1,1] neg_lo:[0,1] neg_hi:[0,1]
	v_add_u32_e32 v62, 0x1a680, v165
	v_exp_f32_e32 v216, v216
	v_exp_f32_e32 v217, v217
	v_exp_f32_e32 v218, v218
	v_exp_f32_e32 v219, v219
	s_waitcnt lgkmcnt(0)
	v_mfma_f32_16x16x32_bf16 v[58:61], v[156:159], v[160:163], v[58:61]
	ds_read_b32 v62, v62
	v_add_u32_e32 v64, v115, v195
	s_nop 5
	v_pk_mul_f32 v[58:59], v[58:59], v[216:217]
	v_pk_mul_f32 v[60:61], v[60:61], v[218:219]
	s_waitcnt lgkmcnt(0)
	v_pk_mul_f32 v[58:59], v[62:63], v[58:59] op_sel_hi:[0,1]
	v_pk_mul_f32 v[60:61], v[62:63], v[60:61] op_sel_hi:[0,1]
	v_cndmask_b32_e64 v58, v58, 0, s[48:49]
	v_cndmask_b32_e64 v59, v59, 0, s[50:51]
	v_cndmask_b32_e64 v60, v60, 0, s[52:53]
	v_cndmask_b32_e64 v61, v61, 0, s[54:55]
	v_cvt_pk_bf16_f32 v58, v58, v59
	v_cvt_pk_bf16_f32 v60, v60, v61
	ds_write_b16 v64, v58 offset:9216
	ds_write_b16_d16_hi v64, v58 offset:9360
	ds_write_b16 v64, v60 offset:9504
	ds_write_b16_d16_hi v64, v60 offset:9648
	s_waitcnt lgkmcnt(0)
	s_barrier
	v_mov_b32_e32 v58, s65
	ds_read_b32 v102, v58
	ds_read_b128 v[148:151], v147
	ds_read_b128 v[176:179], v137 offset:53248
	ds_read_b128 v[180:183], v139 offset:53248
	ds_read_b128 v[184:187], v141 offset:53248
	ds_read_b128 v[188:191], v143 offset:53248
	ds_read_b128 v[152:155], v147 offset:64
	ds_read_b128 v[216:219], v138 offset:53248
	ds_read_b128 v[220:223], v140 offset:53248
	ds_read_b128 v[224:227], v142 offset:53248
	ds_read_b128 v[228:231], v144 offset:53248
	ds_read_b128 v[156:159], v147 offset:9216
	ds_read_b128 v[160:163], v147 offset:9280
	s_waitcnt lgkmcnt(12)
	v_exp_f32_e32 v102, v102
	s_nop 0
	v_pk_mul_f32 v[66:67], v[66:67], v[102:103] op_sel_hi:[1,0]
	v_pk_mul_f32 v[68:69], v[68:69], v[102:103] op_sel_hi:[1,0]
	v_pk_mul_f32 v[78:79], v[78:79], v[102:103] op_sel_hi:[1,0]
	v_pk_mul_f32 v[80:81], v[80:81], v[102:103] op_sel_hi:[1,0]
	v_pk_mul_f32 v[70:71], v[70:71], v[102:103] op_sel_hi:[1,0]
	v_pk_mul_f32 v[72:73], v[72:73], v[102:103] op_sel_hi:[1,0]
	v_pk_mul_f32 v[74:75], v[74:75], v[102:103] op_sel_hi:[1,0]
	v_pk_mul_f32 v[76:77], v[76:77], v[102:103] op_sel_hi:[1,0]
	s_waitcnt lgkmcnt(11)
	s_waitcnt lgkmcnt(10)
	v_mfma_f32_16x16x32_bf16 v[66:69], v[176:179], v[148:151], v[66:69]
	s_waitcnt lgkmcnt(9)
	v_mfma_f32_16x16x32_bf16 v[78:81], v[180:183], v[148:151], v[78:81]
	s_waitcnt lgkmcnt(8)
	v_mfma_f32_16x16x32_bf16 v[70:73], v[184:187], v[148:151], v[70:73]
	s_waitcnt lgkmcnt(7)
	v_mfma_f32_16x16x32_bf16 v[74:77], v[188:191], v[148:151], v[74:77]
	ds_read_b128 v[232:235], v164 offset:18432
	ds_read_b128 v[236:239], v164 offset:18496
	ds_read_b128 v[240:243], v164 offset:18560
	ds_read_b128 v[244:247], v164 offset:18624
	ds_read_b128 v[176:179], v127
	ds_read_b128 v[180:183], v127 offset:64
	ds_read_b128 v[184:187], v127 offset:128
	ds_read_b128 v[188:191], v127 offset:192
	s_waitcnt lgkmcnt(14)
	s_waitcnt lgkmcnt(13)
	v_mfma_f32_16x16x32_bf16 v[66:69], v[216:219], v[152:155], v[66:69]
	s_waitcnt lgkmcnt(12)
	v_mfma_f32_16x16x32_bf16 v[78:81], v[220:223], v[152:155], v[78:81]
	s_waitcnt lgkmcnt(11)
	v_mfma_f32_16x16x32_bf16 v[70:73], v[224:227], v[152:155], v[70:73]
	s_waitcnt lgkmcnt(10)
; #define LAS __attribute__((address_space(3)))
; __device__ __forceinline__ bf16_t f2bf(float f) { return (bf16_t)(pk2(f, 0.f) & 0xffffu); }
; __device__ __forceinline__ float bflo(unsigned w) { return __uint_as_float(w << 16); }
; __device__ __forceinline__ float bfhi(unsigned w) { return __uint_as_float(w & 0xffff0000u); }
; __device__ __forceinline__ void ssd_item(const Args& a, LAS unsigned char* lds, int layer, bool is_sample, int b, int h, int seq_row0, int nchunks,
;                                          bf16_t* proj, float* ssq, const int tid) {
;     ...
;             float sq[4] = {0.f, 0.f, 0.f, 0.f}, el[4];
; #pragma unroll
;             for (int j = 0; j < 4; ++j) el[j] = __builtin_amdgcn_exp2f(acv[16 * rb + 4 * fq + j]);
; #pragma unroll
;             for (int ci = 0; ci < 2; ++ci) { const int cbk = (wave & 1) * 2 + ci; f32x4 acc = (f32x4){0.f, 0.f, 0.f, 0.f}, acp = (f32x4){0.f, 0.f, 0.f, 0.f};
; #pragma unroll
;                 for (int ks = 0; ks < 2; ++ks) { const bf16x8 av = *(const LAS bf16x8*)(lds + L_G + (16 * rb + fr) * P64 + (32 * ks + 8 * fq) * 2);
;                     const bf16x8 bv = *(const LAS bf16x8*)(lds + L_XST + (16 * cbk + fr) * P64 + (32 * ks + 8 * fq) * 2); acc = mfma16(av, bv, acc); }
; #pragma unroll
;                 for (int ks = 0; ks < 4; ++ks) { const bf16x8 av = *(const LAS bf16x8*)(lds + L_CM + (16 * rb + fr) * P128 + (32 * ks + 8 * fq) * 2);
;                     const bf16x8 bv = *(const LAS bf16x8*)(lds + L_ST + (16 * cbk + fr) * P128 + (32 * ks + 8 * fq) * 2); acp = mfma16(av, bv, acp); }
;                 const int p = 16 * cbk + fr;
;                 const u32x2 xs4 = *(const LAS u32x2*)(lds + L_XST + p * P64 + (16 * rb + 4 * fq) * 2);
;                 const float xsv[4] = {bflo(xs4.x), bfhi(xs4.x), bflo(xs4.y), bfhi(xs4.y)};
; #pragma unroll
;                 for (int j = 0; j < 4; ++j) { const int l = 16 * rb + 4 * fq + j;
;                     LAS bf16_t* zp = (LAS bf16_t*)(lds + L_ZT + l * P64 + p * 2);
;                     const float z = bf2f(*zp);
;                     const float yg = (acc[j] + el[j] * acp[j] + xsv[j] * dsk) * siluf_(z);
;                     *zp = f2bf(yg); sq[j] += yg * yg; } }
; #pragma unroll
;             for (int j = 0; j < 4; ++j) { const float v = row16_sum(sq[j]);
;                 if (fr == 0) ssqp[(16 * rb + 4 * fq + j) * 2 + (wave & 1)] = v; }
	v_mfma_f32_16x16x32_bf16 v[74:77], v[228:231], v[152:155], v[74:77]
	ds_read_b128 v[148:151], v126
	ds_read_b128 v[152:155], v126 offset:64
	ds_read_b64 v[248:249], v128
	ds_read_b64 v[250:251], v128 offset:2304
	s_waitcnt lgkmcnt(7)
	v_mfma_f32_16x16x32_bf16 v[176:179], v[232:235], v[176:179], 0
	ds_read_b128 v[216:219], v131
	ds_read_b128 v[220:223], v131 offset:64
	ds_read_b128 v[224:227], v131 offset:128
	ds_read_b128 v[228:231], v131 offset:192
	ds_read_b128 v[58:61], v130
	ds_read_b128 v[62:65], v130 offset:64
	s_waitcnt lgkmcnt(12)
	v_mfma_f32_16x16x32_bf16 v[176:179], v[236:239], v[180:183], v[176:179]
	s_waitcnt lgkmcnt(11)
	v_mfma_f32_16x16x32_bf16 v[176:179], v[240:243], v[184:187], v[176:179]
	s_waitcnt lgkmcnt(10)
	v_mfma_f32_16x16x32_bf16 v[176:179], v[244:247], v[188:191], v[176:179]
	s_waitcnt lgkmcnt(9)
	v_mfma_f32_16x16x32_bf16 v[148:151], v[156:159], v[148:151], 0
	ds_read_u16 v165, v129
	ds_read_u16 v169, v129 offset:144
	ds_read_u16 v170, v129 offset:288
	ds_read_u16 v171, v129 offset:432
	s_waitcnt lgkmcnt(12)
	v_mfma_f32_16x16x32_bf16 v[148:151], v[160:163], v[152:155], v[148:151]
	s_waitcnt lgkmcnt(9)
	v_mfma_f32_16x16x32_bf16 v[216:219], v[232:235], v[216:219], 0
	ds_read_b128 v[232:235], v103
	ds_read_u16 v172, v132
	ds_read_u16 v173, v132 offset:144
	ds_read_u16 v215, v132 offset:288
	ds_read_u16 v102, v132 offset:432
	s_waitcnt lgkmcnt(13)
	v_mfma_f32_16x16x32_bf16 v[216:219], v[236:239], v[220:223], v[216:219]
	s_waitcnt lgkmcnt(10)
	v_mfma_f32_16x16x32_bf16 v[58:61], v[156:159], v[58:61], 0
	s_waitcnt lgkmcnt(9)
	v_mfma_f32_16x16x32_bf16 v[58:61], v[160:163], v[62:65], v[58:61]
	s_waitcnt lgkmcnt(4)
	v_exp_f32_e32 v232, v232
	v_exp_f32_e32 v233, v233
	v_exp_f32_e32 v234, v234
	v_exp_f32_e32 v235, v235
	v_mfma_f32_16x16x32_bf16 v[216:219], v[240:243], v[224:227], v[216:219]
	v_lshlrev_b32_e32 v180, 16, v248
	v_and_b32_e32 v181, 0xffff0000, v248
	v_lshlrev_b32_e32 v182, 16, v249
	v_and_b32_e32 v183, 0xffff0000, v249
	v_mfma_f32_16x16x32_bf16 v[216:219], v[244:247], v[228:231], v[216:219]
	v_lshlrev_b32_e32 v184, 16, v165
	v_lshlrev_b32_e32 v185, 16, v169
	v_lshlrev_b32_e32 v186, 16, v170
	v_lshlrev_b32_e32 v187, 16, v171
	v_mul_f32_e32 v188, 0xbfb8aa3b, v184
	v_mul_f32_e32 v189, 0xbfb8aa3b, v185
	v_mul_f32_e32 v190, 0xbfb8aa3b, v186
	v_mul_f32_e32 v191, 0xbfb8aa3b, v187
	v_exp_f32_e32 v188, v188
	v_exp_f32_e32 v189, v189
	v_exp_f32_e32 v190, v190
	v_exp_f32_e32 v191, v191
	v_pk_fma_f32 v[148:149], v[232:233], v[176:177], v[148:149]
	v_pk_fma_f32 v[150:151], v[234:235], v[178:179], v[150:151]
	v_pk_fma_f32 v[148:149], v[180:181], v[94:95], v[148:149] op_sel:[0,1,0] op_sel_hi:[1,1,1]
	v_pk_fma_f32 v[150:151], v[182:183], v[94:95], v[150:151] op_sel:[0,1,0] op_sel_hi:[1,1,1]
	v_pk_add_f32 v[188:189], v[188:189], 1.0 op_sel_hi:[1,0]
	v_pk_add_f32 v[190:191], v[190:191], 1.0 op_sel_hi:[1,0]
	v_rcp_f32_e32 v188, v188
	v_rcp_f32_e32 v189, v189
	v_rcp_f32_e32 v190, v190
	v_rcp_f32_e32 v191, v191
	v_pk_mul_f32 v[188:189], v[188:189], v[184:185]
	v_pk_mul_f32 v[190:191], v[190:191], v[186:187]
	v_pk_mul_f32 v[152:153], v[148:149], v[188:189]
	v_pk_mul_f32 v[154:155], v[150:151], v[190:191]
	v_cvt_pk_bf16_f32 v176, v152, v1
	ds_write_b16 v129, v176
	v_cvt_pk_bf16_f32 v177, v153, v1
	ds_write_b16 v129, v177 offset:144
	v_cvt_pk_bf16_f32 v178, v154, v1
	ds_write_b16 v129, v178 offset:288
	v_cvt_pk_bf16_f32 v179, v155, v1
	ds_write_b16 v129, v179 offset:432
	v_lshlrev_b32_e32 v184, 16, v250
	v_and_b32_e32 v185, 0xffff0000, v250
	v_lshlrev_b32_e32 v186, 16, v251
	v_and_b32_e32 v187, 0xffff0000, v251
	s_waitcnt lgkmcnt(7)
	v_lshlrev_b32_e32 v180, 16, v172
	s_waitcnt lgkmcnt(6)
	v_lshlrev_b32_e32 v181, 16, v173
	s_waitcnt lgkmcnt(5)
	v_lshlrev_b32_e32 v182, 16, v215
	s_waitcnt lgkmcnt(4)
	v_lshlrev_b32_e32 v183, 16, v102
	v_mul_f32_e32 v188, 0xbfb8aa3b, v180
	v_mul_f32_e32 v189, 0xbfb8aa3b, v181
	v_mul_f32_e32 v190, 0xbfb8aa3b, v182
	v_mul_f32_e32 v191, 0xbfb8aa3b, v183
	v_exp_f32_e32 v188, v188
	v_exp_f32_e32 v189, v189
	v_exp_f32_e32 v190, v190
	v_exp_f32_e32 v191, v191
	v_pk_fma_f32 v[58:59], v[232:233], v[216:217], v[58:59]
	v_pk_fma_f32 v[60:61], v[234:235], v[218:219], v[60:61]
	v_pk_fma_f32 v[58:59], v[184:185], v[94:95], v[58:59] op_sel:[0,1,0] op_sel_hi:[1,1,1]
	v_pk_fma_f32 v[60:61], v[186:187], v[94:95], v[60:61] op_sel:[0,1,0] op_sel_hi:[1,1,1]
	v_pk_add_f32 v[188:189], v[188:189], 1.0 op_sel_hi:[1,0]
	v_pk_add_f32 v[190:191], v[190:191], 1.0 op_sel_hi:[1,0]
	v_rcp_f32_e32 v188, v188
	v_rcp_f32_e32 v189, v189
	v_rcp_f32_e32 v190, v190
	v_rcp_f32_e32 v191, v191
	v_pk_mul_f32 v[188:189], v[188:189], v[180:181]
	v_pk_mul_f32 v[190:191], v[190:191], v[182:183]
	v_pk_mul_f32 v[62:63], v[58:59], v[188:189]
	v_pk_mul_f32 v[64:65], v[60:61], v[190:191]
	v_cvt_pk_bf16_f32 v220, v62, v1
	ds_write_b16 v132, v220
	v_cvt_pk_bf16_f32 v221, v63, v1
	ds_write_b16 v132, v221 offset:144
	v_cvt_pk_bf16_f32 v222, v64, v1
	ds_write_b16 v132, v222 offset:288
	v_cvt_pk_bf16_f32 v223, v65, v1
	ds_write_b16 v132, v223 offset:432
	v_pk_mul_f32 v[156:157], v[62:63], v[62:63]
	v_pk_mul_f32 v[158:159], v[64:65], v[64:65]
	v_pk_fma_f32 v[156:157], v[152:153], v[152:153], v[156:157]
	v_pk_fma_f32 v[158:159], v[154:155], v[154:155], v[158:159]
	s_nop 0
	v_add_f32_dpp v156, v156, v156 quad_perm:[1,0,3,2] row_mask:0xf bank_mask:0xf bound_ctrl:1
	v_add_f32_dpp v157, v157, v157 quad_perm:[1,0,3,2] row_mask:0xf bank_mask:0xf bound_ctrl:1
	v_add_f32_dpp v158, v158, v158 quad_perm:[1,0,3,2] row_mask:0xf bank_mask:0xf bound_ctrl:1
	v_add_f32_dpp v159, v159, v159 quad_perm:[1,0,3,2] row_mask:0xf bank_mask:0xf bound_ctrl:1
	v_add_f32_dpp v156, v156, v156 quad_perm:[2,3,0,1] row_mask:0xf bank_mask:0xf bound_ctrl:1
	v_add_f32_dpp v157, v157, v157 quad_perm:[2,3,0,1] row_mask:0xf bank_mask:0xf bound_ctrl:1
	v_add_f32_dpp v158, v158, v158 quad_perm:[2,3,0,1] row_mask:0xf bank_mask:0xf bound_ctrl:1
	v_add_f32_dpp v159, v159, v159 quad_perm:[2,3,0,1] row_mask:0xf bank_mask:0xf bound_ctrl:1
	v_add_f32_dpp v156, v156, v156 row_half_mirror row_mask:0xf bank_mask:0xf bound_ctrl:1
	v_add_f32_dpp v157, v157, v157 row_half_mirror row_mask:0xf bank_mask:0xf bound_ctrl:1
	v_add_f32_dpp v158, v158, v158 row_half_mirror row_mask:0xf bank_mask:0xf bound_ctrl:1
	v_add_f32_dpp v159, v159, v159 row_half_mirror row_mask:0xf bank_mask:0xf bound_ctrl:1
	v_mov_b32_dpp v160, v156 row_mirror row_mask:0xf bank_mask:0xf bound_ctrl:1
	v_mov_b32_dpp v161, v157 row_mirror row_mask:0xf bank_mask:0xf bound_ctrl:1
	v_mov_b32_dpp v162, v158 row_mirror row_mask:0xf bank_mask:0xf bound_ctrl:1
	v_mov_b32_dpp v163, v159 row_mirror row_mask:0xf bank_mask:0xf bound_ctrl:1
	s_and_saveexec_b64 s[20:21], s[6:7]
	v_add_f32_e32 v156, v156, v160
	v_add_f32_e32 v157, v157, v161
	v_add_f32_e32 v158, v158, v162
	v_add_f32_e32 v159, v159, v163
	ds_write_b32 v133, v156
	ds_write_b32 v134, v157
	ds_write_b32 v135, v158
	ds_write_b32 v136, v159
	s_or_b64 exec, exec, s[20:21]
	s_waitcnt lgkmcnt(0)
	s_barrier
; #define LAS __attribute__((address_space(3)))
; #define LBAR() do { asm volatile("s_waitcnt lgkmcnt(0)" ::: "memory"); __builtin_amdgcn_s_barrier(); asm volatile("" ::: "memory"); } while (0)
; __device__ __forceinline__ void ssd_item(const Args& a, LAS unsigned char* lds, int layer, bool is_sample, int b, int h, int seq_row0, int nchunks,
;                                          bf16_t* proj, float* ssq, const int tid) {
;     ...
;         LBAR();
;         if (tid < 64) ((LAS float*)(lds + L_SSQA))[c * 64 + tid] = ssqp[tid * 2] + ssqp[tid * 2 + 1];
	s_and_saveexec_b64 s[20:21], s[38:39]
	s_cbranch_execz .LBB0_560
	s_nop 1
	ds_read_b64 v[58:59], v145
	v_add_u32_e32 v60, s15, v116
	s_waitcnt lgkmcnt(0)
	v_add_f32_e32 v58, v58, v59
	ds_write_b32 v60, v58
	s_branch .LBB0_560
